# P9 main EpiGu hid stores with nt (streaming) hint to protect operand L2 residency
# speedup vs baseline: 1.0019x; 1.0015x over previous
.LBB0_1243:
	ds_read_b128 v[170:173], v162
	ds_read_b128 v[174:177], v162 offset:1024
	ds_read_b128 v[178:181], v162 offset:2048
	ds_read_b128 v[182:185], v162 offset:3072
	s_add_u32 s34, s30, 0xfffc0080
	s_addc_u32 s35, s31, -1
	s_cmp_eq_u32 s41, 12
	s_cselect_b32 s37, s11, s35
	s_cselect_b32 s36, s17, s34
	s_cselect_b32 s35, s29, s40
	s_cselect_b32 s34, s38, s39
	v_lshl_add_u64 v[144:145], s[30:31], 0, v[134:135]
	s_add_i32 m0, s48, 0xc000
	ds_read_b128 v[186:189], v163
	ds_read_b128 v[190:193], v163 offset:1024
	ds_read_b128 v[194:197], v163 offset:2048
	ds_read_b128 v[198:201], v163 offset:3072
	ds_read_b128 v[204:207], v163 offset:4096
	ds_read_b128 v[208:211], v163 offset:5120
	ds_read_b128 v[212:215], v163 offset:6144
	ds_read_b128 v[216:219], v163 offset:7168
	global_load_lds_dwordx4 v[144:145], off
	v_lshl_add_u64 v[144:145], s[30:31], 0, v[136:137]
	s_add_i32 m0, s48, 0xe000
	s_nop 0
	global_load_lds_dwordx4 v[144:145], off
	ds_read_b128 v[220:223], v164
	ds_read_b128 v[224:227], v164 offset:1024
	ds_read_b128 v[228:231], v164 offset:2048
	ds_read_b128 v[232:235], v164 offset:3072
	s_waitcnt lgkmcnt(0)
	s_waitcnt vmcnt(8)
	s_barrier
	s_setprio 1
	v_mfma_f32_16x16x32_bf16 v[124:127], v[170:173], v[186:189], v[124:127]
	v_mfma_f32_16x16x32_bf16 v[120:123], v[178:181], v[186:189], v[120:123]
	v_mfma_f32_16x16x32_bf16 v[112:115], v[170:173], v[194:197], v[112:115]
	v_mfma_f32_16x16x32_bf16 v[104:107], v[178:181], v[194:197], v[104:107]
	v_mfma_f32_16x16x32_bf16 v[96:99], v[170:173], v[204:207], v[96:99]
	v_mfma_f32_16x16x32_bf16 v[88:91], v[178:181], v[204:207], v[88:91]
	v_mfma_f32_16x16x32_bf16 v[80:83], v[170:173], v[212:215], v[80:83]
	v_mfma_f32_16x16x32_bf16 v[72:75], v[178:181], v[212:215], v[72:75]
	v_mfma_f32_16x16x32_bf16 v[124:127], v[174:177], v[190:193], v[124:127]
	v_mfma_f32_16x16x32_bf16 v[120:123], v[182:185], v[190:193], v[120:123]
	v_mfma_f32_16x16x32_bf16 v[112:115], v[174:177], v[198:201], v[112:115]
	v_mfma_f32_16x16x32_bf16 v[104:107], v[182:185], v[198:201], v[104:107]
	v_mfma_f32_16x16x32_bf16 v[96:99], v[174:177], v[208:211], v[96:99]
	v_mfma_f32_16x16x32_bf16 v[88:91], v[182:185], v[208:211], v[88:91]
	v_mfma_f32_16x16x32_bf16 v[80:83], v[174:177], v[216:219], v[80:83]
	v_mfma_f32_16x16x32_bf16 v[72:75], v[182:185], v[216:219], v[72:75]
	v_mfma_f32_16x16x32_bf16 v[116:119], v[220:223], v[186:189], v[116:119]
	v_mfma_f32_16x16x32_bf16 v[108:111], v[228:231], v[186:189], v[108:111]
	v_mfma_f32_16x16x32_bf16 v[100:103], v[220:223], v[194:197], v[100:103]
	v_mfma_f32_16x16x32_bf16 v[92:95], v[228:231], v[194:197], v[92:95]
	v_mfma_f32_16x16x32_bf16 v[84:87], v[220:223], v[204:207], v[84:87]
	v_mfma_f32_16x16x32_bf16 v[76:79], v[228:231], v[204:207], v[76:79]
	v_mfma_f32_16x16x32_bf16 v[68:71], v[220:223], v[212:215], v[68:71]
	v_mfma_f32_16x16x32_bf16 v[64:67], v[228:231], v[212:215], v[64:67]
	v_mfma_f32_16x16x32_bf16 v[116:119], v[224:227], v[190:193], v[116:119]
	v_mfma_f32_16x16x32_bf16 v[108:111], v[232:235], v[190:193], v[108:111]
	v_mfma_f32_16x16x32_bf16 v[100:103], v[224:227], v[198:201], v[100:103]
	v_mfma_f32_16x16x32_bf16 v[92:95], v[232:235], v[198:201], v[92:95]
	v_mfma_f32_16x16x32_bf16 v[84:87], v[224:227], v[208:211], v[84:87]
	v_mfma_f32_16x16x32_bf16 v[76:79], v[232:235], v[208:211], v[76:79]
	v_mfma_f32_16x16x32_bf16 v[68:71], v[224:227], v[216:219], v[68:71]
	v_mfma_f32_16x16x32_bf16 v[64:67], v[232:235], v[216:219], v[64:67]
	s_setprio 0
	s_barrier
	ds_read_b128 v[186:189], v163 offset:16384
	ds_read_b128 v[190:193], v163 offset:17408
	ds_read_b128 v[194:197], v163 offset:18432
	ds_read_b128 v[198:201], v163 offset:19456
	ds_read_b128 v[204:207], v163 offset:20480
	ds_read_b128 v[208:211], v163 offset:21504
	ds_read_b128 v[212:215], v163 offset:22528
	ds_read_b128 v[216:219], v163 offset:23552
	s_mov_b32 m0, s46
	v_lshl_add_u64 v[144:145], s[34:35], 0, v[128:129]
	global_load_lds_dwordx4 v[144:145], off
	v_lshl_add_u64 v[236:237], s[34:35], 0, v[130:131]
	s_mov_b32 m0, s47
	s_nop 0
	global_load_lds_dwordx4 v[236:237], off
	s_mov_b32 m0, s48
	v_lshl_add_u64 v[238:239], s[36:37], 0, v[128:129]
	global_load_lds_dwordx4 v[238:239], off
	v_lshl_add_u64 v[240:241], s[36:37], 0, v[130:131]
	s_mov_b32 m0, s49
	s_nop 0
	global_load_lds_dwordx4 v[240:241], off
	s_add_u32 s72, s34, 0x40000
	s_addc_u32 s73, s35, 0
	s_mov_b32 m0, s50
	v_lshl_add_u64 v[248:249], s[72:73], 0, v[128:129]
	global_load_lds_dwordx4 v[248:249], off
	v_lshl_add_u64 v[248:249], s[72:73], 0, v[130:131]
	s_mov_b32 m0, s51
	s_nop 0
	global_load_lds_dwordx4 v[248:249], off
	s_waitcnt lgkmcnt(0)
	s_waitcnt vmcnt(8)
	s_barrier
	s_setprio 1
	v_mfma_f32_16x16x32_bf16 v[60:63], v[170:173], v[186:189], v[60:63]
	v_mfma_f32_16x16x32_bf16 v[56:59], v[178:181], v[186:189], v[56:59]
	v_mfma_f32_16x16x32_bf16 v[48:51], v[170:173], v[194:197], v[48:51]
	v_mfma_f32_16x16x32_bf16 v[40:43], v[178:181], v[194:197], v[40:43]
	v_mfma_f32_16x16x32_bf16 v[32:35], v[170:173], v[204:207], v[32:35]
	v_mfma_f32_16x16x32_bf16 v[24:27], v[178:181], v[204:207], v[24:27]
	v_mfma_f32_16x16x32_bf16 v[16:19], v[170:173], v[212:215], v[16:19]
	v_mfma_f32_16x16x32_bf16 v[8:11], v[178:181], v[212:215], v[8:11]
	v_mfma_f32_16x16x32_bf16 v[60:63], v[174:177], v[190:193], v[60:63]
	v_mfma_f32_16x16x32_bf16 v[56:59], v[182:185], v[190:193], v[56:59]
	v_mfma_f32_16x16x32_bf16 v[48:51], v[174:177], v[198:201], v[48:51]
	v_mfma_f32_16x16x32_bf16 v[40:43], v[182:185], v[198:201], v[40:43]
	v_mfma_f32_16x16x32_bf16 v[32:35], v[174:177], v[208:211], v[32:35]
	v_mfma_f32_16x16x32_bf16 v[24:27], v[182:185], v[208:211], v[24:27]
	v_mfma_f32_16x16x32_bf16 v[16:19], v[174:177], v[216:219], v[16:19]
	v_mfma_f32_16x16x32_bf16 v[8:11], v[182:185], v[216:219], v[8:11]
	v_mfma_f32_16x16x32_bf16 v[52:55], v[220:223], v[186:189], v[52:55]
	v_mfma_f32_16x16x32_bf16 v[44:47], v[228:231], v[186:189], v[44:47]
	v_mfma_f32_16x16x32_bf16 v[36:39], v[220:223], v[194:197], v[36:39]
	v_mfma_f32_16x16x32_bf16 v[28:31], v[228:231], v[194:197], v[28:31]
	v_mfma_f32_16x16x32_bf16 v[20:23], v[220:223], v[204:207], v[20:23]
	v_mfma_f32_16x16x32_bf16 v[12:15], v[228:231], v[204:207], v[12:15]
	v_mfma_f32_16x16x32_bf16 v[4:7], v[220:223], v[212:215], v[4:7]
	v_mfma_f32_16x16x32_bf16 v[0:3], v[228:231], v[212:215], v[0:3]
	v_mfma_f32_16x16x32_bf16 v[52:55], v[224:227], v[190:193], v[52:55]
	v_mfma_f32_16x16x32_bf16 v[44:47], v[232:235], v[190:193], v[44:47]
	v_mfma_f32_16x16x32_bf16 v[36:39], v[224:227], v[198:201], v[36:39]
	v_mfma_f32_16x16x32_bf16 v[28:31], v[232:235], v[198:201], v[28:31]
	v_mfma_f32_16x16x32_bf16 v[20:23], v[224:227], v[208:211], v[20:23]
	v_mfma_f32_16x16x32_bf16 v[12:15], v[232:235], v[208:211], v[12:15]
	v_mfma_f32_16x16x32_bf16 v[4:7], v[224:227], v[216:219], v[4:7]
	v_mfma_f32_16x16x32_bf16 v[0:3], v[232:235], v[216:219], v[0:3]
	s_setprio 0
	s_barrier
	ds_read_b128 v[170:173], v165
	ds_read_b128 v[174:177], v165 offset:1024
	ds_read_b128 v[178:181], v165 offset:2048
	ds_read_b128 v[182:185], v165 offset:3072
	s_add_u32 s36, s36, 0x40000
	s_addc_u32 s37, s37, 0
	s_mov_b32 m0, s52
	v_lshl_add_u64 v[220:221], s[36:37], 0, v[128:129]
	ds_read_b128 v[186:189], v163 offset:32768
	ds_read_b128 v[190:193], v163 offset:33792
	ds_read_b128 v[194:197], v163 offset:34816
	ds_read_b128 v[198:201], v163 offset:35840
	ds_read_b128 v[204:207], v163 offset:36864
	ds_read_b128 v[208:211], v163 offset:37888
	ds_read_b128 v[212:215], v163 offset:38912
	ds_read_b128 v[216:219], v163 offset:39936
	global_load_lds_dwordx4 v[220:221], off
	v_lshl_add_u64 v[220:221], s[36:37], 0, v[130:131]
	s_mov_b32 m0, s53
	s_nop 0
	global_load_lds_dwordx4 v[220:221], off
	ds_read_b128 v[220:223], v166
	ds_read_b128 v[224:227], v166 offset:1024
	ds_read_b128 v[228:231], v166 offset:2048
	ds_read_b128 v[232:235], v166 offset:3072
	s_waitcnt lgkmcnt(0)
	s_waitcnt vmcnt(8)
	s_barrier
	s_setprio 1
	v_mfma_f32_16x16x32_bf16 v[124:127], v[170:173], v[186:189], v[124:127]
	v_mfma_f32_16x16x32_bf16 v[120:123], v[178:181], v[186:189], v[120:123]
	v_mfma_f32_16x16x32_bf16 v[112:115], v[170:173], v[194:197], v[112:115]
	v_mfma_f32_16x16x32_bf16 v[104:107], v[178:181], v[194:197], v[104:107]
	v_mfma_f32_16x16x32_bf16 v[96:99], v[170:173], v[204:207], v[96:99]
	v_mfma_f32_16x16x32_bf16 v[88:91], v[178:181], v[204:207], v[88:91]
	v_mfma_f32_16x16x32_bf16 v[80:83], v[170:173], v[212:215], v[80:83]
	v_mfma_f32_16x16x32_bf16 v[72:75], v[178:181], v[212:215], v[72:75]
	v_mfma_f32_16x16x32_bf16 v[124:127], v[174:177], v[190:193], v[124:127]
	v_mfma_f32_16x16x32_bf16 v[120:123], v[182:185], v[190:193], v[120:123]
	v_mfma_f32_16x16x32_bf16 v[112:115], v[174:177], v[198:201], v[112:115]
	v_mfma_f32_16x16x32_bf16 v[104:107], v[182:185], v[198:201], v[104:107]
	v_mfma_f32_16x16x32_bf16 v[96:99], v[174:177], v[208:211], v[96:99]
	v_mfma_f32_16x16x32_bf16 v[88:91], v[182:185], v[208:211], v[88:91]
	v_mfma_f32_16x16x32_bf16 v[80:83], v[174:177], v[216:219], v[80:83]
	v_mfma_f32_16x16x32_bf16 v[72:75], v[182:185], v[216:219], v[72:75]
	v_mfma_f32_16x16x32_bf16 v[116:119], v[220:223], v[186:189], v[116:119]
	v_mfma_f32_16x16x32_bf16 v[108:111], v[228:231], v[186:189], v[108:111]
	v_mfma_f32_16x16x32_bf16 v[100:103], v[220:223], v[194:197], v[100:103]
	v_mfma_f32_16x16x32_bf16 v[92:95], v[228:231], v[194:197], v[92:95]
	v_mfma_f32_16x16x32_bf16 v[84:87], v[220:223], v[204:207], v[84:87]
	v_mfma_f32_16x16x32_bf16 v[76:79], v[228:231], v[204:207], v[76:79]
	v_mfma_f32_16x16x32_bf16 v[68:71], v[220:223], v[212:215], v[68:71]
	v_mfma_f32_16x16x32_bf16 v[64:67], v[228:231], v[212:215], v[64:67]
	v_mfma_f32_16x16x32_bf16 v[116:119], v[224:227], v[190:193], v[116:119]
	v_mfma_f32_16x16x32_bf16 v[108:111], v[232:235], v[190:193], v[108:111]
	v_mfma_f32_16x16x32_bf16 v[100:103], v[224:227], v[198:201], v[100:103]
	v_mfma_f32_16x16x32_bf16 v[92:95], v[232:235], v[198:201], v[92:95]
	v_mfma_f32_16x16x32_bf16 v[84:87], v[224:227], v[208:211], v[84:87]
	v_mfma_f32_16x16x32_bf16 v[76:79], v[232:235], v[208:211], v[76:79]
	v_mfma_f32_16x16x32_bf16 v[68:71], v[224:227], v[216:219], v[68:71]
	v_mfma_f32_16x16x32_bf16 v[64:67], v[232:235], v[216:219], v[64:67]
	s_setprio 0
	s_barrier
	ds_read_b128 v[186:189], v163 offset:49152
	ds_read_b128 v[190:193], v163 offset:50176
	ds_read_b128 v[194:197], v163 offset:51200
	ds_read_b128 v[198:201], v163 offset:52224
	ds_read_b128 v[204:207], v163 offset:53248
	ds_read_b128 v[208:211], v163 offset:54272
	ds_read_b128 v[212:215], v163 offset:55296
	ds_read_b128 v[216:219], v163 offset:56320
	s_mov_b32 m0, s54
	v_lshl_add_u64 v[144:145], v[144:145], 0, s[12:13]
	global_load_lds_dwordx4 v[144:145], off
	v_lshl_add_u64 v[144:145], v[236:237], 0, s[12:13]
	s_mov_b32 m0, s55
	s_nop 0
	global_load_lds_dwordx4 v[144:145], off
	s_mov_b32 m0, s56
	v_lshl_add_u64 v[144:145], v[238:239], 0, s[12:13]
	global_load_lds_dwordx4 v[144:145], off
	v_lshl_add_u64 v[144:145], v[240:241], 0, s[12:13]
	s_mov_b32 m0, s57
	s_nop 0
	global_load_lds_dwordx4 v[144:145], off
	s_add_u32 s34, s34, 0x40080
	s_addc_u32 s35, s35, 0
	s_mov_b32 m0, s58
	v_lshl_add_u64 v[144:145], s[34:35], 0, v[128:129]
	global_load_lds_dwordx4 v[144:145], off
	v_lshl_add_u64 v[144:145], s[34:35], 0, v[130:131]
	s_mov_b32 m0, s59
	s_nop 0
	global_load_lds_dwordx4 v[144:145], off
	s_waitcnt lgkmcnt(0)
	s_waitcnt vmcnt(8)
	s_barrier
	s_setprio 1
	v_mfma_f32_16x16x32_bf16 v[60:63], v[170:173], v[186:189], v[60:63]
	v_mfma_f32_16x16x32_bf16 v[56:59], v[178:181], v[186:189], v[56:59]
	v_mfma_f32_16x16x32_bf16 v[48:51], v[170:173], v[194:197], v[48:51]
	v_mfma_f32_16x16x32_bf16 v[40:43], v[178:181], v[194:197], v[40:43]
	v_mfma_f32_16x16x32_bf16 v[32:35], v[170:173], v[204:207], v[32:35]
	v_mfma_f32_16x16x32_bf16 v[24:27], v[178:181], v[204:207], v[24:27]
	v_mfma_f32_16x16x32_bf16 v[16:19], v[170:173], v[212:215], v[16:19]
	v_mfma_f32_16x16x32_bf16 v[8:11], v[178:181], v[212:215], v[8:11]
	v_mfma_f32_16x16x32_bf16 v[60:63], v[174:177], v[190:193], v[60:63]
	v_mfma_f32_16x16x32_bf16 v[56:59], v[182:185], v[190:193], v[56:59]
	v_mfma_f32_16x16x32_bf16 v[48:51], v[174:177], v[198:201], v[48:51]
	v_mfma_f32_16x16x32_bf16 v[40:43], v[182:185], v[198:201], v[40:43]
	v_mfma_f32_16x16x32_bf16 v[32:35], v[174:177], v[208:211], v[32:35]
	v_mfma_f32_16x16x32_bf16 v[24:27], v[182:185], v[208:211], v[24:27]
	v_mfma_f32_16x16x32_bf16 v[16:19], v[174:177], v[216:219], v[16:19]
	v_mfma_f32_16x16x32_bf16 v[8:11], v[182:185], v[216:219], v[8:11]
	v_mfma_f32_16x16x32_bf16 v[52:55], v[220:223], v[186:189], v[52:55]
	v_mfma_f32_16x16x32_bf16 v[44:47], v[228:231], v[186:189], v[44:47]
	v_mfma_f32_16x16x32_bf16 v[36:39], v[220:223], v[194:197], v[36:39]
	v_mfma_f32_16x16x32_bf16 v[28:31], v[228:231], v[194:197], v[28:31]
	v_mfma_f32_16x16x32_bf16 v[20:23], v[220:223], v[204:207], v[20:23]
	v_mfma_f32_16x16x32_bf16 v[12:15], v[228:231], v[204:207], v[12:15]
	v_mfma_f32_16x16x32_bf16 v[4:7], v[220:223], v[212:215], v[4:7]
	v_mfma_f32_16x16x32_bf16 v[0:3], v[228:231], v[212:215], v[0:3]
	v_mfma_f32_16x16x32_bf16 v[52:55], v[224:227], v[190:193], v[52:55]
	v_mfma_f32_16x16x32_bf16 v[44:47], v[232:235], v[190:193], v[44:47]
	v_mfma_f32_16x16x32_bf16 v[36:39], v[224:227], v[198:201], v[36:39]
	v_mfma_f32_16x16x32_bf16 v[28:31], v[232:235], v[198:201], v[28:31]
	v_mfma_f32_16x16x32_bf16 v[20:23], v[224:227], v[208:211], v[20:23]
	v_mfma_f32_16x16x32_bf16 v[12:15], v[232:235], v[208:211], v[12:15]
	v_mfma_f32_16x16x32_bf16 v[4:7], v[224:227], v[216:219], v[4:7]
	v_mfma_f32_16x16x32_bf16 v[0:3], v[232:235], v[216:219], v[0:3]
	s_setprio 0
	s_add_i32 s41, s41, 2
	s_add_u32 s30, s30, 0x100
	s_addc_u32 s31, s31, 0
	s_add_u32 s39, s39, 0x100
	s_addc_u32 s40, s40, 0
	s_cmp_gt_u32 s41, 13
	s_barrier
	s_cbranch_scc0 .LBB0_1243
	s_cmpk_lt_i32 s42, 0x80
	s_cbranch_scc0 .Lgu_sample
	v_lshlrev_b32_e32 v170, 2, v160
	v_add_u32_e32 v170, s92, v170
	ds_read_b32 v174, v170
	ds_read_b32 v176, v170 offset:64
	ds_read_b32 v156, v170 offset:128
	ds_read_b32 v154, v170 offset:192
	ds_read_b32 v152, v170 offset:512
	ds_read_b32 v150, v170 offset:576
	ds_read_b32 v148, v170 offset:640
	ds_read_b32 v146, v170 offset:704
	v_lshl_add_u32 v144, s42, 8, v160
	v_add_u32_e32 v145, 0x80, v144
	s_cmpk_lt_i32 s42, 0x80
	s_waitcnt lgkmcnt(0)
	v_pk_mul_f32 v[124:125], v[124:125], v[174:175] op_sel_hi:[1,0]
	v_mul_f32_e32 v172, 0xbfb8aa3b, v125
	v_exp_f32_e32 v173, v172
	v_mul_f32_e32 v169, 0xbfb8aa3b, v124
	v_exp_f32_e32 v169, v169
	v_pk_mul_f32 v[126:127], v[126:127], v[174:175] op_sel_hi:[1,0]
	v_pk_mul_f32 v[118:119], v[118:119], v[174:175] op_sel_hi:[1,0]
	v_add_f32_e32 v169, 1.0, v169
	v_rcp_f32_e32 v172, v169
	v_add_f32_e32 v169, 1.0, v173
	v_mul_f32_e32 v173, 0xbfb8aa3b, v126
	v_exp_f32_e32 v175, v173
	v_mul_f32_e32 v173, 0xbfb8aa3b, v127
	v_exp_f32_e32 v177, v173
	v_rcp_f32_e32 v173, v169
	v_add_f32_e32 v169, 1.0, v175
	v_rcp_f32_e32 v178, v169
	v_add_f32_e32 v169, 1.0, v177
	v_rcp_f32_e32 v179, v169
	v_pk_mul_f32 v[116:117], v[116:117], v[174:175] op_sel_hi:[1,0]
	v_pk_mul_f32 v[124:125], v[124:125], v[172:173]
	v_pk_mul_f32 v[120:121], v[120:121], v[174:175] op_sel_hi:[1,0]
	v_pk_mul_f32 v[116:117], v[116:117], v[124:125]
	v_pk_mul_f32 v[124:125], v[126:127], v[178:179]
	v_pk_mul_f32 v[122:123], v[122:123], v[174:175] op_sel_hi:[1,0]
	v_pk_mul_f32 v[118:119], v[118:119], v[124:125]
	v_mul_f32_e32 v124, 0xbfb8aa3b, v120
	v_mul_f32_e32 v125, 0xbfb8aa3b, v121
	v_exp_f32_e32 v124, v124
	v_exp_f32_e32 v125, v125
	v_mul_f32_e32 v126, 0xbfb8aa3b, v122
	v_mul_f32_e32 v127, 0xbfb8aa3b, v123
	v_exp_f32_e32 v126, v126
	v_exp_f32_e32 v127, v127
	v_add_f32_e32 v124, 1.0, v124
	v_add_f32_e32 v125, 1.0, v125
	v_rcp_f32_e32 v124, v124
	v_rcp_f32_e32 v125, v125
	v_add_f32_e32 v126, 1.0, v126
	v_add_f32_e32 v127, 1.0, v127
	v_rcp_f32_e32 v126, v126
	v_rcp_f32_e32 v127, v127
	v_pk_mul_f32 v[108:109], v[108:109], v[174:175] op_sel_hi:[1,0]
	v_pk_mul_f32 v[120:121], v[120:121], v[124:125]
	v_lshl_or_b32 v170, s28, 7, v161
	v_pk_mul_f32 v[110:111], v[110:111], v[174:175] op_sel_hi:[1,0]
	v_pk_mul_f32 v[108:109], v[108:109], v[120:121]
	v_pk_mul_f32 v[120:121], v[122:123], v[126:127]
	v_ashrrev_i32_e32 v171, 31, v170
	v_pk_mul_f32 v[110:111], v[110:111], v[120:121]
	v_cvt_pk_bf16_f32 v116, v116, v117
	v_cvt_pk_bf16_f32 v117, v118, v119
	v_cvt_pk_bf16_f32 v118, v108, v109
	v_mov_b64_e32 v[108:109], s[6:7]
	v_cvt_pk_bf16_f32 v119, v110, v111
	v_mad_i64_i32 v[120:121], s[28:29], v144, s68, v[108:109]
	v_lshlrev_b64 v[110:111], 1, v[170:171]
	v_lshl_add_u64 v[120:121], v[120:121], 0, v[110:111]
	v_pk_mul_f32 v[112:113], v[112:113], v[176:177] op_sel_hi:[1,0]
	global_store_dwordx4 v[120:121], v[116:119], off nt
	v_pk_mul_f32 v[114:115], v[114:115], v[176:177] op_sel_hi:[1,0]
	v_pk_mul_f32 v[100:101], v[100:101], v[176:177] op_sel_hi:[1,0]
	v_mul_f32_e32 v116, 0xbfb8aa3b, v112
	v_mul_f32_e32 v117, 0xbfb8aa3b, v113
	v_exp_f32_e32 v116, v116
	v_exp_f32_e32 v117, v117
	v_mul_f32_e32 v118, 0xbfb8aa3b, v114
	v_mul_f32_e32 v119, 0xbfb8aa3b, v115
	v_exp_f32_e32 v118, v118
	v_exp_f32_e32 v119, v119
	v_add_f32_e32 v116, 1.0, v116
	v_add_f32_e32 v117, 1.0, v117
	v_rcp_f32_e32 v116, v116
	v_rcp_f32_e32 v117, v117
	v_add_f32_e32 v118, 1.0, v118
	v_add_f32_e32 v119, 1.0, v119
	v_rcp_f32_e32 v118, v118
	v_rcp_f32_e32 v119, v119
	v_pk_mul_f32 v[112:113], v[112:113], v[116:117]
	v_pk_mul_f32 v[102:103], v[102:103], v[176:177] op_sel_hi:[1,0]
	v_pk_mul_f32 v[100:101], v[100:101], v[112:113]
	v_pk_mul_f32 v[112:113], v[114:115], v[118:119]
	v_pk_mul_f32 v[104:105], v[104:105], v[176:177] op_sel_hi:[1,0]
	v_pk_mul_f32 v[102:103], v[102:103], v[112:113]
	v_pk_mul_f32 v[106:107], v[106:107], v[176:177] op_sel_hi:[1,0]
	v_mul_f32_e32 v112, 0xbfb8aa3b, v104
	v_mul_f32_e32 v113, 0xbfb8aa3b, v105
	v_exp_f32_e32 v112, v112
	v_exp_f32_e32 v113, v113
	v_mul_f32_e32 v114, 0xbfb8aa3b, v106
	v_mul_f32_e32 v115, 0xbfb8aa3b, v107
	v_exp_f32_e32 v114, v114
	v_exp_f32_e32 v115, v115
	v_add_f32_e32 v112, 1.0, v112
	v_add_f32_e32 v113, 1.0, v113
	v_rcp_f32_e32 v112, v112
	v_rcp_f32_e32 v113, v113
	v_add_f32_e32 v114, 1.0, v114
	v_add_f32_e32 v115, 1.0, v115
	v_rcp_f32_e32 v114, v114
	v_rcp_f32_e32 v115, v115
	v_pk_mul_f32 v[92:93], v[92:93], v[176:177] op_sel_hi:[1,0]
	v_pk_mul_f32 v[104:105], v[104:105], v[112:113]
	v_pk_mul_f32 v[94:95], v[94:95], v[176:177] op_sel_hi:[1,0]
	v_pk_mul_f32 v[104:105], v[92:93], v[104:105]
	v_pk_mul_f32 v[92:93], v[106:107], v[114:115]
	v_or_b32_e32 v112, 16, v144
	v_pk_mul_f32 v[106:107], v[94:95], v[92:93]
	v_cvt_pk_bf16_f32 v92, v100, v101
	v_mad_i64_i32 v[100:101], s[28:29], v112, s68, v[108:109]
	v_cvt_pk_bf16_f32 v93, v102, v103
	v_cvt_pk_bf16_f32 v94, v104, v105
	v_cvt_pk_bf16_f32 v95, v106, v107
	v_lshl_add_u64 v[100:101], v[100:101], 0, v[110:111]
	global_store_dwordx4 v[100:101], v[92:95], off nt
	v_pk_mul_f32 v[86:87], v[86:87], v[156:157] op_sel_hi:[1,0]
	v_pk_mul_f32 v[88:89], v[88:89], v[156:157] op_sel_hi:[1,0]
	v_pk_mul_f32 v[92:93], v[98:99], v[156:157] op_sel_hi:[1,0]
	v_pk_mul_f32 v[94:95], v[96:97], v[156:157] op_sel_hi:[1,0]
	v_mul_f32_e32 v98, 0xbfb8aa3b, v92
	v_mul_f32_e32 v99, 0xbfb8aa3b, v93
	v_mul_f32_e32 v96, 0xbfb8aa3b, v94
	v_mul_f32_e32 v97, 0xbfb8aa3b, v95
	v_exp_f32_e32 v98, v98
	v_exp_f32_e32 v99, v99
	v_exp_f32_e32 v96, v96
	v_exp_f32_e32 v97, v97
	v_add_f32_e32 v98, 1.0, v98
	v_add_f32_e32 v99, 1.0, v99
	v_add_f32_e32 v96, 1.0, v96
	v_add_f32_e32 v97, 1.0, v97
	v_rcp_f32_e32 v98, v98
	v_rcp_f32_e32 v99, v99
	v_rcp_f32_e32 v96, v96
	v_rcp_f32_e32 v97, v97
	v_pk_mul_f32 v[84:85], v[84:85], v[156:157] op_sel_hi:[1,0]
	v_pk_mul_f32 v[92:93], v[92:93], v[98:99]
	v_pk_mul_f32 v[90:91], v[90:91], v[156:157] op_sel_hi:[1,0]
	v_pk_mul_f32 v[94:95], v[94:95], v[96:97]
	v_pk_mul_f32 v[86:87], v[86:87], v[92:93]
	v_mul_f32_e32 v92, 0xbfb8aa3b, v88
	v_mul_f32_e32 v93, 0xbfb8aa3b, v89
	v_pk_mul_f32 v[84:85], v[84:85], v[94:95]
	v_exp_f32_e32 v92, v92
	v_exp_f32_e32 v93, v93
	v_mul_f32_e32 v94, 0xbfb8aa3b, v90
	v_mul_f32_e32 v95, 0xbfb8aa3b, v91
	v_exp_f32_e32 v94, v94
	v_exp_f32_e32 v95, v95
	v_add_f32_e32 v92, 1.0, v92
	v_add_f32_e32 v93, 1.0, v93
	v_rcp_f32_e32 v92, v92
	v_rcp_f32_e32 v93, v93
	v_add_f32_e32 v94, 1.0, v94
	v_add_f32_e32 v95, 1.0, v95
	v_rcp_f32_e32 v94, v94
	v_rcp_f32_e32 v95, v95
	v_pk_mul_f32 v[76:77], v[76:77], v[156:157] op_sel_hi:[1,0]
	v_pk_mul_f32 v[88:89], v[88:89], v[92:93]
	v_pk_mul_f32 v[78:79], v[78:79], v[156:157] op_sel_hi:[1,0]
	v_pk_mul_f32 v[88:89], v[76:77], v[88:89]
	v_pk_mul_f32 v[76:77], v[90:91], v[94:95]
	v_or_b32_e32 v92, 32, v144
	v_pk_mul_f32 v[90:91], v[78:79], v[76:77]
	v_cvt_pk_bf16_f32 v76, v84, v85
	v_mad_i64_i32 v[84:85], s[28:29], v92, s68, v[108:109]
	v_cvt_pk_bf16_f32 v77, v86, v87
	v_cvt_pk_bf16_f32 v78, v88, v89
	v_cvt_pk_bf16_f32 v79, v90, v91
	v_lshl_add_u64 v[84:85], v[84:85], 0, v[110:111]
	global_store_dwordx4 v[84:85], v[76:79], off nt
	v_pk_mul_f32 v[70:71], v[70:71], v[154:155] op_sel_hi:[1,0]
	v_pk_mul_f32 v[72:73], v[72:73], v[154:155] op_sel_hi:[1,0]
	v_pk_mul_f32 v[76:77], v[82:83], v[154:155] op_sel_hi:[1,0]
	v_pk_mul_f32 v[78:79], v[80:81], v[154:155] op_sel_hi:[1,0]
	v_mul_f32_e32 v82, 0xbfb8aa3b, v76
	v_mul_f32_e32 v83, 0xbfb8aa3b, v77
	v_mul_f32_e32 v80, 0xbfb8aa3b, v78
	v_mul_f32_e32 v81, 0xbfb8aa3b, v79
	v_exp_f32_e32 v82, v82
	v_exp_f32_e32 v83, v83
	v_exp_f32_e32 v80, v80
	v_exp_f32_e32 v81, v81
	v_add_f32_e32 v82, 1.0, v82
	v_add_f32_e32 v83, 1.0, v83
	v_add_f32_e32 v80, 1.0, v80
	v_add_f32_e32 v81, 1.0, v81
	v_rcp_f32_e32 v82, v82
	v_rcp_f32_e32 v83, v83
	v_rcp_f32_e32 v80, v80
	v_rcp_f32_e32 v81, v81
	v_pk_mul_f32 v[68:69], v[68:69], v[154:155] op_sel_hi:[1,0]
	v_pk_mul_f32 v[76:77], v[76:77], v[82:83]
	v_pk_mul_f32 v[74:75], v[74:75], v[154:155] op_sel_hi:[1,0]
	v_pk_mul_f32 v[78:79], v[78:79], v[80:81]
	v_pk_mul_f32 v[70:71], v[70:71], v[76:77]
	v_mul_f32_e32 v76, 0xbfb8aa3b, v72
	v_mul_f32_e32 v77, 0xbfb8aa3b, v73
	v_pk_mul_f32 v[68:69], v[68:69], v[78:79]
	v_exp_f32_e32 v76, v76
	v_exp_f32_e32 v77, v77
	v_mul_f32_e32 v78, 0xbfb8aa3b, v74
	v_mul_f32_e32 v79, 0xbfb8aa3b, v75
	v_exp_f32_e32 v78, v78
	v_exp_f32_e32 v79, v79
	v_add_f32_e32 v76, 1.0, v76
	v_add_f32_e32 v77, 1.0, v77
	v_rcp_f32_e32 v76, v76
	v_rcp_f32_e32 v77, v77
	v_add_f32_e32 v78, 1.0, v78
	v_add_f32_e32 v79, 1.0, v79
	v_rcp_f32_e32 v78, v78
	v_rcp_f32_e32 v79, v79
	v_pk_mul_f32 v[64:65], v[64:65], v[154:155] op_sel_hi:[1,0]
	v_pk_mul_f32 v[72:73], v[72:73], v[76:77]
	v_pk_mul_f32 v[66:67], v[66:67], v[154:155] op_sel_hi:[1,0]
	v_pk_mul_f32 v[72:73], v[64:65], v[72:73]
	v_pk_mul_f32 v[64:65], v[74:75], v[78:79]
	v_or_b32_e32 v76, 48, v144
	v_pk_mul_f32 v[74:75], v[66:67], v[64:65]
	v_cvt_pk_bf16_f32 v64, v68, v69
	v_mad_i64_i32 v[68:69], s[28:29], v76, s68, v[108:109]
	v_cvt_pk_bf16_f32 v65, v70, v71
	v_cvt_pk_bf16_f32 v66, v72, v73
	v_cvt_pk_bf16_f32 v67, v74, v75
	v_lshl_add_u64 v[68:69], v[68:69], 0, v[110:111]
	v_pk_mul_f32 v[60:61], v[60:61], v[152:153] op_sel_hi:[1,0]
	global_store_dwordx4 v[68:69], v[64:67], off nt
	v_pk_mul_f32 v[62:63], v[62:63], v[152:153] op_sel_hi:[1,0]
	v_pk_mul_f32 v[52:53], v[52:53], v[152:153] op_sel_hi:[1,0]
	v_mul_f32_e32 v64, 0xbfb8aa3b, v60
	v_mul_f32_e32 v65, 0xbfb8aa3b, v61
	v_exp_f32_e32 v64, v64
	v_exp_f32_e32 v65, v65
	v_mul_f32_e32 v66, 0xbfb8aa3b, v62
	v_mul_f32_e32 v67, 0xbfb8aa3b, v63
	v_exp_f32_e32 v66, v66
	v_exp_f32_e32 v67, v67
	v_add_f32_e32 v64, 1.0, v64
	v_add_f32_e32 v65, 1.0, v65
	v_rcp_f32_e32 v64, v64
	v_rcp_f32_e32 v65, v65
	v_add_f32_e32 v66, 1.0, v66
	v_add_f32_e32 v67, 1.0, v67
	v_rcp_f32_e32 v66, v66
	v_rcp_f32_e32 v67, v67
	v_pk_mul_f32 v[60:61], v[60:61], v[64:65]
	v_pk_mul_f32 v[54:55], v[54:55], v[152:153] op_sel_hi:[1,0]
	v_pk_mul_f32 v[52:53], v[52:53], v[60:61]
	v_pk_mul_f32 v[60:61], v[62:63], v[66:67]
	v_pk_mul_f32 v[56:57], v[56:57], v[152:153] op_sel_hi:[1,0]
	v_pk_mul_f32 v[54:55], v[54:55], v[60:61]
	v_pk_mul_f32 v[58:59], v[58:59], v[152:153] op_sel_hi:[1,0]
	v_mul_f32_e32 v60, 0xbfb8aa3b, v56
	v_mul_f32_e32 v61, 0xbfb8aa3b, v57
	v_exp_f32_e32 v60, v60
	v_exp_f32_e32 v61, v61
	v_mul_f32_e32 v62, 0xbfb8aa3b, v58
	v_mul_f32_e32 v63, 0xbfb8aa3b, v59
	v_exp_f32_e32 v62, v62
	v_exp_f32_e32 v63, v63
	v_add_f32_e32 v60, 1.0, v60
	v_add_f32_e32 v61, 1.0, v61
	v_rcp_f32_e32 v60, v60
	v_rcp_f32_e32 v61, v61
	v_add_f32_e32 v62, 1.0, v62
	v_add_f32_e32 v63, 1.0, v63
	v_rcp_f32_e32 v62, v62
	v_rcp_f32_e32 v63, v63
	v_pk_mul_f32 v[44:45], v[44:45], v[152:153] op_sel_hi:[1,0]
	v_pk_mul_f32 v[56:57], v[56:57], v[60:61]
	v_pk_mul_f32 v[46:47], v[46:47], v[152:153] op_sel_hi:[1,0]
	v_pk_mul_f32 v[56:57], v[44:45], v[56:57]
	v_pk_mul_f32 v[44:45], v[58:59], v[62:63]
	v_pk_mul_f32 v[38:39], v[38:39], v[150:151] op_sel_hi:[1,0]
	v_pk_mul_f32 v[58:59], v[46:47], v[44:45]
	v_cvt_pk_bf16_f32 v44, v52, v53
	v_mad_i64_i32 v[52:53], s[28:29], v145, s68, v[108:109]
	v_cvt_pk_bf16_f32 v45, v54, v55
	v_cvt_pk_bf16_f32 v46, v56, v57
	v_cvt_pk_bf16_f32 v47, v58, v59
	v_lshl_add_u64 v[52:53], v[52:53], 0, v[110:111]
	global_store_dwordx4 v[52:53], v[44:47], off nt
	v_pk_mul_f32 v[40:41], v[40:41], v[150:151] op_sel_hi:[1,0]
	v_pk_mul_f32 v[36:37], v[36:37], v[150:151] op_sel_hi:[1,0]
	v_pk_mul_f32 v[44:45], v[50:51], v[150:151] op_sel_hi:[1,0]
	v_pk_mul_f32 v[46:47], v[48:49], v[150:151] op_sel_hi:[1,0]
	v_mul_f32_e32 v50, 0xbfb8aa3b, v44
	v_mul_f32_e32 v51, 0xbfb8aa3b, v45
	v_mul_f32_e32 v48, 0xbfb8aa3b, v46
	v_mul_f32_e32 v49, 0xbfb8aa3b, v47
	v_exp_f32_e32 v50, v50
	v_exp_f32_e32 v51, v51
	v_exp_f32_e32 v48, v48
	v_exp_f32_e32 v49, v49
	v_add_f32_e32 v50, 1.0, v50
	v_add_f32_e32 v51, 1.0, v51
	v_add_f32_e32 v48, 1.0, v48
	v_add_f32_e32 v49, 1.0, v49
	v_rcp_f32_e32 v50, v50
	v_rcp_f32_e32 v51, v51
	v_rcp_f32_e32 v48, v48
	v_rcp_f32_e32 v49, v49
	v_pk_mul_f32 v[42:43], v[42:43], v[150:151] op_sel_hi:[1,0]
	v_pk_mul_f32 v[44:45], v[44:45], v[50:51]
	v_pk_mul_f32 v[46:47], v[46:47], v[48:49]
	v_pk_mul_f32 v[38:39], v[38:39], v[44:45]
	v_mul_f32_e32 v44, 0xbfb8aa3b, v40
	v_mul_f32_e32 v45, 0xbfb8aa3b, v41
	v_pk_mul_f32 v[36:37], v[36:37], v[46:47]
	v_exp_f32_e32 v44, v44
	v_exp_f32_e32 v45, v45
	v_mul_f32_e32 v46, 0xbfb8aa3b, v42
	v_mul_f32_e32 v47, 0xbfb8aa3b, v43
	v_exp_f32_e32 v46, v46
	v_exp_f32_e32 v47, v47
	v_add_f32_e32 v44, 1.0, v44
	v_add_f32_e32 v45, 1.0, v45
	v_rcp_f32_e32 v44, v44
	v_rcp_f32_e32 v45, v45
	v_add_f32_e32 v46, 1.0, v46
	v_add_f32_e32 v47, 1.0, v47
	v_rcp_f32_e32 v46, v46
	v_rcp_f32_e32 v47, v47
	v_pk_mul_f32 v[28:29], v[28:29], v[150:151] op_sel_hi:[1,0]
	v_pk_mul_f32 v[40:41], v[40:41], v[44:45]
	v_pk_mul_f32 v[30:31], v[30:31], v[150:151] op_sel_hi:[1,0]
	v_pk_mul_f32 v[40:41], v[28:29], v[40:41]
	v_pk_mul_f32 v[28:29], v[42:43], v[46:47]
	v_add_u32_e32 v44, 0x90, v144
	v_pk_mul_f32 v[42:43], v[30:31], v[28:29]
	v_cvt_pk_bf16_f32 v28, v36, v37
	v_mad_i64_i32 v[36:37], s[28:29], v44, s68, v[108:109]
	v_cvt_pk_bf16_f32 v29, v38, v39
	v_cvt_pk_bf16_f32 v30, v40, v41
	v_cvt_pk_bf16_f32 v31, v42, v43
	v_lshl_add_u64 v[36:37], v[36:37], 0, v[110:111]
	global_store_dwordx4 v[36:37], v[28:31], off nt
	v_pk_mul_f32 v[22:23], v[22:23], v[148:149] op_sel_hi:[1,0]
	v_pk_mul_f32 v[24:25], v[24:25], v[148:149] op_sel_hi:[1,0]
	v_pk_mul_f32 v[28:29], v[34:35], v[148:149] op_sel_hi:[1,0]
	v_pk_mul_f32 v[30:31], v[32:33], v[148:149] op_sel_hi:[1,0]
	v_mul_f32_e32 v34, 0xbfb8aa3b, v28
	v_mul_f32_e32 v35, 0xbfb8aa3b, v29
	v_mul_f32_e32 v32, 0xbfb8aa3b, v30
	v_mul_f32_e32 v33, 0xbfb8aa3b, v31
	v_exp_f32_e32 v34, v34
	v_exp_f32_e32 v35, v35
	v_exp_f32_e32 v32, v32
	v_exp_f32_e32 v33, v33
	v_add_f32_e32 v34, 1.0, v34
	v_add_f32_e32 v35, 1.0, v35
	v_add_f32_e32 v32, 1.0, v32
	v_add_f32_e32 v33, 1.0, v33
	v_rcp_f32_e32 v34, v34
	v_rcp_f32_e32 v35, v35
	v_rcp_f32_e32 v32, v32
	v_rcp_f32_e32 v33, v33
	v_pk_mul_f32 v[20:21], v[20:21], v[148:149] op_sel_hi:[1,0]
	v_pk_mul_f32 v[28:29], v[28:29], v[34:35]
	v_pk_mul_f32 v[26:27], v[26:27], v[148:149] op_sel_hi:[1,0]
	v_pk_mul_f32 v[30:31], v[30:31], v[32:33]
	v_pk_mul_f32 v[22:23], v[22:23], v[28:29]
	v_mul_f32_e32 v28, 0xbfb8aa3b, v24
	v_mul_f32_e32 v29, 0xbfb8aa3b, v25
	v_pk_mul_f32 v[20:21], v[20:21], v[30:31]
	v_exp_f32_e32 v28, v28
	v_exp_f32_e32 v29, v29
	v_mul_f32_e32 v30, 0xbfb8aa3b, v26
	v_mul_f32_e32 v31, 0xbfb8aa3b, v27
	v_exp_f32_e32 v30, v30
	v_exp_f32_e32 v31, v31
	v_add_f32_e32 v28, 1.0, v28
	v_add_f32_e32 v29, 1.0, v29
	v_rcp_f32_e32 v28, v28
	v_rcp_f32_e32 v29, v29
	v_add_f32_e32 v30, 1.0, v30
	v_add_f32_e32 v31, 1.0, v31
	v_rcp_f32_e32 v30, v30
	v_rcp_f32_e32 v31, v31
	v_pk_mul_f32 v[12:13], v[12:13], v[148:149] op_sel_hi:[1,0]
	v_pk_mul_f32 v[24:25], v[24:25], v[28:29]
	v_pk_mul_f32 v[14:15], v[14:15], v[148:149] op_sel_hi:[1,0]
	v_pk_mul_f32 v[24:25], v[12:13], v[24:25]
	v_pk_mul_f32 v[12:13], v[26:27], v[30:31]
	v_add_u32_e32 v28, 0xa0, v144
	v_pk_mul_f32 v[26:27], v[14:15], v[12:13]
	v_cvt_pk_bf16_f32 v12, v20, v21
	v_mad_i64_i32 v[20:21], s[28:29], v28, s68, v[108:109]
	v_cvt_pk_bf16_f32 v13, v22, v23
	v_cvt_pk_bf16_f32 v14, v24, v25
	v_cvt_pk_bf16_f32 v15, v26, v27
	v_lshl_add_u64 v[20:21], v[20:21], 0, v[110:111]
	global_store_dwordx4 v[20:21], v[12:15], off nt
	v_pk_mul_f32 v[6:7], v[6:7], v[146:147] op_sel_hi:[1,0]
	v_pk_mul_f32 v[8:9], v[8:9], v[146:147] op_sel_hi:[1,0]
	v_pk_mul_f32 v[12:13], v[18:19], v[146:147] op_sel_hi:[1,0]
	v_pk_mul_f32 v[14:15], v[16:17], v[146:147] op_sel_hi:[1,0]
	v_mul_f32_e32 v18, 0xbfb8aa3b, v12
	v_mul_f32_e32 v19, 0xbfb8aa3b, v13
	v_mul_f32_e32 v16, 0xbfb8aa3b, v14
	v_mul_f32_e32 v17, 0xbfb8aa3b, v15
	v_exp_f32_e32 v18, v18
	v_exp_f32_e32 v19, v19
	v_exp_f32_e32 v16, v16
	v_exp_f32_e32 v17, v17
	v_add_f32_e32 v18, 1.0, v18
	v_add_f32_e32 v19, 1.0, v19
	v_add_f32_e32 v16, 1.0, v16
	v_add_f32_e32 v17, 1.0, v17
	v_rcp_f32_e32 v18, v18
	v_rcp_f32_e32 v19, v19
	v_rcp_f32_e32 v16, v16
	v_rcp_f32_e32 v17, v17
	v_pk_mul_f32 v[4:5], v[4:5], v[146:147] op_sel_hi:[1,0]
	v_pk_mul_f32 v[12:13], v[12:13], v[18:19]
	v_pk_mul_f32 v[10:11], v[10:11], v[146:147] op_sel_hi:[1,0]
	v_pk_mul_f32 v[14:15], v[14:15], v[16:17]
	v_pk_mul_f32 v[6:7], v[6:7], v[12:13]
	v_mul_f32_e32 v12, 0xbfb8aa3b, v8
	v_mul_f32_e32 v13, 0xbfb8aa3b, v9
	v_pk_mul_f32 v[4:5], v[4:5], v[14:15]
	v_exp_f32_e32 v12, v12
	v_exp_f32_e32 v13, v13
	v_mul_f32_e32 v14, 0xbfb8aa3b, v10
	v_mul_f32_e32 v15, 0xbfb8aa3b, v11
	v_exp_f32_e32 v14, v14
	v_exp_f32_e32 v15, v15
	v_add_f32_e32 v12, 1.0, v12
	v_add_f32_e32 v13, 1.0, v13
	v_rcp_f32_e32 v12, v12
	v_rcp_f32_e32 v13, v13
	v_add_f32_e32 v14, 1.0, v14
	v_add_f32_e32 v15, 1.0, v15
	v_rcp_f32_e32 v14, v14
	v_rcp_f32_e32 v15, v15
	v_pk_mul_f32 v[0:1], v[0:1], v[146:147] op_sel_hi:[1,0]
	v_pk_mul_f32 v[8:9], v[8:9], v[12:13]
	v_pk_mul_f32 v[2:3], v[2:3], v[146:147] op_sel_hi:[1,0]
	v_pk_mul_f32 v[8:9], v[0:1], v[8:9]
	v_pk_mul_f32 v[0:1], v[10:11], v[14:15]
	v_add_u32_e32 v12, 0xb0, v144
	v_pk_mul_f32 v[10:11], v[2:3], v[0:1]
	v_cvt_pk_bf16_f32 v0, v4, v5
	v_mad_i64_i32 v[4:5], s[28:29], v12, s68, v[108:109]
	v_cvt_pk_bf16_f32 v1, v6, v7
	v_cvt_pk_bf16_f32 v2, v8, v9
	v_cvt_pk_bf16_f32 v3, v10, v11
	v_lshl_add_u64 v[4:5], v[4:5], 0, v[110:111]
	global_store_dwordx4 v[4:5], v[0:3], off nt
	s_cbranch_scc1 .LBB0_1226
	s_waitcnt vmcnt(0)
	buffer_wbl2 sc1
	s_waitcnt vmcnt(0)
	s_waitcnt vmcnt(0)
	s_and_saveexec_b64 s[28:29], s[4:5]
	s_cbranch_execz .LBB0_1225
	s_mov_b64 s[30:31], exec
	v_mbcnt_lo_u32_b32 v0, s30, 0
	v_mbcnt_hi_u32_b32 v0, s31, v0
	v_cmp_eq_u32_e32 vcc, 0, v0
	s_and_b64 s[34:35], exec, vcc
	s_mov_b64 exec, s[34:35]
	s_cbranch_execz .LBB0_1225
	s_bcnt1_i32_b64 s11, s[30:31]
	v_mov_b32_e32 v0, s11
	global_atomic_add v129, v0, s[8:9]
	s_branch .LBB0_1225
